# v7 + attention unit start waits only for the prefetched Q/tile-0 loads (vmcnt 8), not for the previous unit's output stores
# baseline (speedup 1.0000x reference)
.LBB0_1508:
	s_waitcnt vmcnt(0)
	s_bfe_u32 s45, s2, 0x40003
	s_xor_b32 s46, s45, 15
	s_lshr_b32 s47, s2, 7
	s_mov_b32 s12, 0
	s_movk_i32 s52, 0x190
	v_mov_b32_e32 v165, 0
	s_mov_b32 s53, 0x40000
	s_mov_b32 s54, 0x60000
	s_movk_i32 s55, 0x2000
	s_mov_b32 s56, 0x80000
	s_movk_i32 s57, 0x90
	s_mov_b64 s[6:7], 0x1e004000
	s_mov_b64 s[8:9], 0x80
	s_mov_b64 s[30:31], 0x2000
	s_mov_b64 s[36:37], 0x40000
	s_movk_i32 s58, 0x1800
	v_mov_b32_e32 v180, 0xff800000
	s_mov_b32 s17, 0
	s_branch .LBB0_1510

.LBB0_1518:
	s_mov_b32 s14, s96
	v_mbcnt_lo_u32_b32 v4, -1, 0
	v_mbcnt_hi_u32_b32 v4, -1, v4
	s_and_b32 s21, s16, 7
	v_lshl_add_u32 v1, s14, 6, v4
	s_lshl_b32 s67, s13, 2
	v_readfirstlane_b32 s14, v1
	s_ashr_i32 s66, s14, 1
	s_andn2_b32 s66, s66, 31
	s_lshl_b32 s14, s13, 8
	v_lshlrev_b32_e32 v3, 4, v4
	s_add_i32 s61, s66, s14
	s_add_i32 s67, s67, 4
	s_lshl_b32 s62, s21, 12
	s_lshl_b32 s13, s21, 24
	v_ashrrev_i32_e32 v2, 4, v1
	v_and_b32_e32 v0, 0xf0, v3
	s_add_u32 s18, s34, s13
	v_lshl_or_b32 v164, v2, 12, v0
	v_mad_u64_u32 v[170:171], s[26:27], v2, s52, v[0:1]
	v_lshlrev_b32_e32 v166, 4, v1
	v_ashrrev_i32_e32 v1, 3, v1
	v_and_b32_e32 v0, 0x70, v3
	s_addc_u32 s19, s35, 0
	s_lshl_b32 s14, s60, 7
	v_mad_u64_u32 v[172:173], s[26:27], v1, s52, v[0:1]
	s_ashr_i32 s15, s14, 31
	v_lshl_or_b32 v168, v1, 13, v0
	v_add_u32_e32 v2, 0, v170
	v_add_u32_e32 v0, 0, v172
	s_lshl_b64 s[16:17], s[14:15], 1
	s_waitcnt vmcnt(8)
	ds_write_b128 v2, v[144:147]
	ds_write_b128 v2, v[148:151] offset:12800
	ds_write_b128 v0, v[152:155] offset:256
	v_lshlrev_b32_e32 v0, 8, v1
	s_add_u32 s18, s18, s16
	v_sub_u32_e32 v183, v172, v0
	s_addc_u32 s19, s19, s17
	s_lshl_b32 s20, s21, 19
	v_add_u32_e32 v0, 0, v183
	s_add_u32 s22, s33, s20
	ds_write_b128 v0, v[156:159] offset:25600
	ds_write_b128 v0, v[160:163] offset:34816
	v_lshl_add_u64 v[0:1], s[18:19], 0, v[164:165]
	s_addc_u32 s23, s44, 0
	s_lshl_b32 s15, s21, 11
	v_add_co_u32_e32 v2, vcc, s53, v0
	s_add_i32 s14, s15, s14
	s_nop 0
	v_addc_co_u32_e32 v3, vcc, 0, v1, vcc
	s_ashr_i32 s15, s14, 31
	v_add_co_u32_e32 v0, vcc, s54, v0
	s_lshl_b64 s[14:15], s[14:15], 13
	s_nop 0
	v_addc_co_u32_e32 v1, vcc, 0, v1, vcc
	v_mov_b32_e32 v167, v165
	s_add_u32 s24, s71, s14
	global_load_dwordx4 v[144:147], v[2:3], off
	global_load_dwordx4 v[148:151], v[0:1], off
	v_lshl_add_u64 v[0:1], s[22:23], 0, v[166:167]
	s_addc_u32 s25, s72, s15
	v_add_co_u32_e32 v0, vcc, s55, v0
	v_mov_b32_e32 v169, v165
	s_nop 0
	v_addc_co_u32_e32 v1, vcc, 0, v1, vcc
	v_lshl_add_u64 v[2:3], s[24:25], 0, v[168:169]
	v_add_co_u32_e32 v2, vcc, s56, v2
	global_load_dwordx4 v[156:159], v168, s[24:25] offset:128
	s_nop 0
	v_addc_co_u32_e32 v3, vcc, 0, v3, vcc
	global_load_dwordx4 v[152:155], v[0:1], off
	global_load_dwordx4 v[160:163], v[2:3], off offset:128
	v_bfe_u32 v182, v4, 5, 1
	v_and_b32_e32 v171, 31, v4
	s_mov_b32 s21, s12
	s_or_b32 s68, s61, 31
	v_lshl_add_u32 v0, v182, 4, 0
	v_mad_u32_u24 v185, v171, s52, v0
	v_mad_u32_u24 v186, v171, s57, v0
	v_lshl_add_u64 v[174:175], s[14:15], 0, v[168:169]
	v_lshl_add_u64 v[0:1], v[166:167], 0, s[20:21]
	s_add_u32 s14, s13, s16
	v_mov_b32_e32 v14, v165
	v_mov_b32_e32 v15, v165
	v_lshl_add_u64 v[176:177], v[0:1], 0, s[6:7]
	s_addc_u32 s15, 0, s17
	v_mov_b32_e32 v0, v165
	v_mov_b32_e32 v1, v165
	v_mov_b32_e32 v2, v165
	v_mov_b32_e32 v3, v165
	v_mov_b32_e32 v4, v165
	v_mov_b32_e32 v5, v165
	v_mov_b32_e32 v6, v165
	v_mov_b32_e32 v7, v165
	v_mov_b32_e32 v8, v165
	v_mov_b32_e32 v9, v165
	v_mov_b32_e32 v10, v165
	v_mov_b32_e32 v11, v165
	v_mov_b32_e32 v12, v165
	v_mov_b32_e32 v13, v165
	v_mov_b64_e32 v[30:31], v[14:15]
	v_mov_b64_e32 v[46:47], v[14:15]
	v_mov_b64_e32 v[62:63], v[14:15]
	s_mov_b32 s73, 0
	v_or_b32_e32 v184, s61, v171
	v_lshlrev_b32_e32 v173, 2, v182
	v_lshl_add_u64 v[178:179], s[14:15], 0, v[164:165]
	v_mov_b32_e32 v181, 0
	v_mov_b32_e32 v188, 0xf149f2ca
	s_mov_b32 s69, 63
	v_mov_b64_e32 v[28:29], v[12:13]
	v_mov_b64_e32 v[26:27], v[10:11]
	v_mov_b64_e32 v[24:25], v[8:9]
	v_mov_b64_e32 v[22:23], v[6:7]
	v_mov_b64_e32 v[20:21], v[4:5]
	v_mov_b64_e32 v[18:19], v[2:3]
	v_mov_b64_e32 v[16:17], v[0:1]
	v_mov_b64_e32 v[44:45], v[12:13]
	v_mov_b64_e32 v[42:43], v[10:11]
	v_mov_b64_e32 v[40:41], v[8:9]
	v_mov_b64_e32 v[38:39], v[6:7]
	v_mov_b64_e32 v[36:37], v[4:5]
	v_mov_b64_e32 v[34:35], v[2:3]
	v_mov_b64_e32 v[32:33], v[0:1]
	v_mov_b64_e32 v[60:61], v[12:13]
	v_mov_b64_e32 v[58:59], v[10:11]
	v_mov_b64_e32 v[56:57], v[8:9]
	v_mov_b64_e32 v[54:55], v[6:7]
	v_mov_b64_e32 v[52:53], v[4:5]
	v_mov_b64_e32 v[50:51], v[2:3]
	v_mov_b64_e32 v[48:49], v[0:1]
	s_waitcnt lgkmcnt(0)
	s_barrier
	s_setprio 1
	s_sub_i32 s13, s69, 63
	s_cmp_gt_i32 s13, s68
	s_cbranch_scc0 .LBB0_1525
